# v91 + skinny: the five skinny_sample K-loops software-pipelined (all 4 fragment loads of a k-step together, next k-step prefetched into a second register set; one vmcnt(4) per step instead of two vmcn
# baseline (speedup 1.0000x reference)
.LBB0_526:
	s_ashr_i32 s25, s24, 31
	s_lshl_b64 s[26:27], s[24:25], 1
	v_lshl_add_u64 v[26:27], v[18:19], 0, s[26:27]
	v_lshl_add_u64 v[34:35], v[22:23], 0, s[26:27]
	v_lshl_add_u64 v[30:31], v[20:21], 0, s[26:27]
	v_lshl_add_u64 v[48:49], v[24:25], 0, s[26:27]
	global_load_dwordx4 v[26:29], v[26:27], off
	global_load_dwordx4 v[34:37], v[34:35], off
	global_load_dwordx4 v[30:33], v[30:31], off
	global_load_dwordx4 v[48:51], v[48:49], off
.Lmy_sk0_loop:
	s_add_i32 s21, s21, 8
	s_addk_i32 s24, 0x100
	s_ashr_i32 s25, s24, 31
	s_lshl_b64 s[26:27], s[24:25], 1
	s_cmp_gt_i32 s21, 55
	s_cbranch_scc1 .Lmy_sk0_lastx
	v_lshl_add_u64 v[52:53], v[18:19], 0, s[26:27]
	v_lshl_add_u64 v[56:57], v[22:23], 0, s[26:27]
	v_lshl_add_u64 v[60:61], v[20:21], 0, s[26:27]
	v_lshl_add_u64 v[64:65], v[24:25], 0, s[26:27]
	global_load_dwordx4 v[52:55], v[52:53], off
	global_load_dwordx4 v[56:59], v[56:57], off
	global_load_dwordx4 v[60:63], v[60:61], off
	global_load_dwordx4 v[64:67], v[64:65], off
	s_waitcnt vmcnt(4)
	v_mfma_f32_16x16x32_bf16 v[14:17], v[26:29], v[30:33], v[14:17]
	v_mfma_f32_16x16x32_bf16 v[10:13], v[34:37], v[30:33], v[10:13]
	v_mfma_f32_16x16x32_bf16 v[6:9], v[26:29], v[48:51], v[6:9]
	v_mfma_f32_16x16x32_bf16 v[2:5], v[34:37], v[48:51], v[2:5]
	s_add_i32 s21, s21, 8
	s_addk_i32 s24, 0x100
	s_ashr_i32 s25, s24, 31
	s_lshl_b64 s[26:27], s[24:25], 1
	s_cmp_gt_i32 s21, 55
	s_cbranch_scc1 .Lmy_sk0_lasty
	v_lshl_add_u64 v[26:27], v[18:19], 0, s[26:27]
	v_lshl_add_u64 v[34:35], v[22:23], 0, s[26:27]
	v_lshl_add_u64 v[30:31], v[20:21], 0, s[26:27]
	v_lshl_add_u64 v[48:49], v[24:25], 0, s[26:27]
	global_load_dwordx4 v[26:29], v[26:27], off
	global_load_dwordx4 v[34:37], v[34:35], off
	global_load_dwordx4 v[30:33], v[30:31], off
	global_load_dwordx4 v[48:51], v[48:49], off
	s_waitcnt vmcnt(4)
	v_mfma_f32_16x16x32_bf16 v[14:17], v[52:55], v[60:63], v[14:17]
	v_mfma_f32_16x16x32_bf16 v[10:13], v[56:59], v[60:63], v[10:13]
	v_mfma_f32_16x16x32_bf16 v[6:9], v[52:55], v[64:67], v[6:9]
	v_mfma_f32_16x16x32_bf16 v[2:5], v[56:59], v[64:67], v[2:5]
	s_branch .Lmy_sk0_loop
.Lmy_sk0_lastx:
	s_waitcnt vmcnt(0)
	v_mfma_f32_16x16x32_bf16 v[14:17], v[26:29], v[30:33], v[14:17]
	v_mfma_f32_16x16x32_bf16 v[10:13], v[34:37], v[30:33], v[10:13]
	v_mfma_f32_16x16x32_bf16 v[6:9], v[26:29], v[48:51], v[6:9]
	v_mfma_f32_16x16x32_bf16 v[2:5], v[34:37], v[48:51], v[2:5]
	s_branch .Lmy_sk0_done
.Lmy_sk0_lasty:
	s_waitcnt vmcnt(0)
	v_mfma_f32_16x16x32_bf16 v[14:17], v[52:55], v[60:63], v[14:17]
	v_mfma_f32_16x16x32_bf16 v[10:13], v[56:59], v[60:63], v[10:13]
	v_mfma_f32_16x16x32_bf16 v[6:9], v[52:55], v[64:67], v[6:9]
	v_mfma_f32_16x16x32_bf16 v[2:5], v[56:59], v[64:67], v[2:5]
.Lmy_sk0_done:
.LBB0_527:
	s_lshl_b32 s12, s12, 12
	v_lshlrev_b32_e32 v18, 7, v157
	s_add_i32 s12, s12, 0
	v_add3_u32 v18, s12, v130, v18
	s_movk_i32 s12, 0x100
	v_cmp_gt_i32_e32 vcc, s12, v156
	ds_write_b128 v18, v[14:17]
	ds_write_b128 v18, v[10:13] offset:64
	ds_write_b128 v18, v[6:9] offset:2048
	ds_write_b128 v18, v[2:5] offset:2112
	s_waitcnt lgkmcnt(0)
	s_barrier
	s_and_saveexec_b64 s[24:25], vcc
	s_cbranch_execz .LBB0_532
	v_lshlrev_b32_e32 v2, 2, v156
	v_ashrrev_i32_e32 v12, 3, v156
	v_and_b32_e32 v13, 28, v2
	v_lshlrev_b32_e32 v2, 7, v12
	v_lshlrev_b32_e32 v3, 2, v13
	v_add3_u32 v14, 0, v2, v3
	ds_read_b128 v[2:5], v14
	ds_read_b128 v[6:9], v14 offset:4096
	s_waitcnt lgkmcnt(0)
	v_pk_add_f32 v[8:9], v[4:5], v[8:9]
	v_pk_add_f32 v[6:7], v[2:3], v[6:7]
	ds_read_b128 v[2:5], v14 offset:8192
	s_waitcnt lgkmcnt(0)
	v_pk_add_f32 v[8:9], v[8:9], v[4:5]
	v_pk_add_f32 v[6:7], v[6:7], v[2:3]
	ds_read_b128 v[2:5], v14 offset:12288
	s_waitcnt lgkmcnt(0)
	v_pk_add_f32 v[8:9], v[8:9], v[4:5]
	v_pk_add_f32 v[6:7], v[6:7], v[2:3]
	ds_read_b128 v[2:5], v14 offset:16384
	s_waitcnt lgkmcnt(0)
	v_pk_add_f32 v[8:9], v[8:9], v[4:5]
	v_pk_add_f32 v[6:7], v[6:7], v[2:3]
	ds_read_b128 v[2:5], v14 offset:20480
	s_waitcnt lgkmcnt(0)
	v_pk_add_f32 v[8:9], v[8:9], v[4:5]
	v_pk_add_f32 v[6:7], v[6:7], v[2:3]
	ds_read_b128 v[2:5], v14 offset:24576
	s_waitcnt lgkmcnt(0)
	v_pk_add_f32 v[8:9], v[8:9], v[4:5]
	v_pk_add_f32 v[10:11], v[6:7], v[2:3]
	ds_read_b128 v[4:7], v14 offset:28672
	s_waitcnt lgkmcnt(0)
	v_pk_add_f32 v[2:3], v[8:9], v[6:7]
	v_add_u32_e32 v9, s8, v12
	v_pk_add_f32 v[6:7], v[10:11], v[4:5]
	v_add_u32_e32 v10, 0x2000, v9
	v_ashrrev_i32_e32 v11, 31, v10
	v_lshl_add_u64 v[4:5], v[10:11], 3, s[14:15]
	global_load_dwordx2 v[4:5], v[4:5], off
	v_or_b32_e32 v8, s9, v13
	s_movk_i32 s8, 0x5ff
	s_waitcnt vmcnt(0)
	v_ffbh_u32_e32 v12, v5
	v_min_u32_e32 v12, 32, v12
	v_lshlrev_b64 v[4:5], v12, v[4:5]
	v_min_u32_e32 v4, 1, v4
	v_or_b32_e32 v4, v5, v4
	v_cvt_f32_u32_e32 v4, v4
	v_sub_u32_e32 v5, 32, v12
	v_ldexp_f32 v4, v4, v5
	v_mul_f32_e32 v4, 0x30800000, v4
	v_fmamk_f32 v4, v4, 0x3a000000, v1
	v_cmp_gt_f32_e32 vcc, s65, v4
	v_mul_f32_e32 v5, 0x4b800000, v4
	s_nop 0
	v_cndmask_b32_e32 v4, v4, v5, vcc
	v_rsq_f32_e32 v4, v4
	s_nop 0
	v_mul_f32_e32 v5, 0x45800000, v4
	v_cndmask_b32_e32 v12, v4, v5, vcc
	v_pk_mul_f32 v[4:5], v[2:3], v[12:13] op_sel_hi:[1,0]
	v_pk_mul_f32 v[2:3], v[6:7], v[12:13] op_sel_hi:[1,0]
	v_cmp_lt_i32_e32 vcc, s8, v8
	s_and_saveexec_b64 s[8:9], vcc
	s_xor_b64 s[26:27], exec, s[8:9]
	s_cbranch_execz .LBB0_530
	v_cvt_pk_bf16_f32 v2, v2, v3
	v_cvt_pk_bf16_f32 v3, v4, v5
	v_lshlrev_b64 v[4:5], 10, v[10:11]
	v_lshl_add_u64 v[4:5], s[10:11], 0, v[4:5]
	v_mov_b32_e32 v9, v181
	v_lshl_add_u64 v[4:5], v[8:9], 1, v[4:5]
	global_store_dwordx2 v[4:5], v[2:3], off offset:-3072

.LBB0_722:
	s_ashr_i32 s19, s18, 31
	s_lshl_b64 s[22:23], s[18:19], 1
	v_lshl_add_u64 v[26:27], v[18:19], 0, s[22:23]
	v_lshl_add_u64 v[34:35], v[22:23], 0, s[22:23]
	v_lshl_add_u64 v[30:31], v[20:21], 0, s[22:23]
	v_lshl_add_u64 v[48:49], v[24:25], 0, s[22:23]
	global_load_dwordx4 v[26:29], v[26:27], off
	global_load_dwordx4 v[34:37], v[34:35], off
	global_load_dwordx4 v[30:33], v[30:31], off
	global_load_dwordx4 v[48:51], v[48:49], off
.Lmy_sk1_loop:
	s_add_i32 s6, s6, 8
	s_addk_i32 s18, 0x100
	s_ashr_i32 s19, s18, 31
	s_lshl_b64 s[22:23], s[18:19], 1
	s_cmp_gt_i32 s6, 55
	s_cbranch_scc1 .Lmy_sk1_lastx
	v_lshl_add_u64 v[52:53], v[18:19], 0, s[22:23]
	v_lshl_add_u64 v[56:57], v[22:23], 0, s[22:23]
	v_lshl_add_u64 v[60:61], v[20:21], 0, s[22:23]
	v_lshl_add_u64 v[64:65], v[24:25], 0, s[22:23]
	global_load_dwordx4 v[52:55], v[52:53], off
	global_load_dwordx4 v[56:59], v[56:57], off
	global_load_dwordx4 v[60:63], v[60:61], off
	global_load_dwordx4 v[64:67], v[64:65], off
	s_waitcnt vmcnt(4)
	v_mfma_f32_16x16x32_bf16 v[14:17], v[26:29], v[30:33], v[14:17]
	v_mfma_f32_16x16x32_bf16 v[10:13], v[34:37], v[30:33], v[10:13]
	v_mfma_f32_16x16x32_bf16 v[6:9], v[26:29], v[48:51], v[6:9]
	v_mfma_f32_16x16x32_bf16 v[2:5], v[34:37], v[48:51], v[2:5]
	s_add_i32 s6, s6, 8
	s_addk_i32 s18, 0x100
	s_ashr_i32 s19, s18, 31
	s_lshl_b64 s[22:23], s[18:19], 1
	s_cmp_gt_i32 s6, 55
	s_cbranch_scc1 .Lmy_sk1_lasty
	v_lshl_add_u64 v[26:27], v[18:19], 0, s[22:23]
	v_lshl_add_u64 v[34:35], v[22:23], 0, s[22:23]
	v_lshl_add_u64 v[30:31], v[20:21], 0, s[22:23]
	v_lshl_add_u64 v[48:49], v[24:25], 0, s[22:23]
	global_load_dwordx4 v[26:29], v[26:27], off
	global_load_dwordx4 v[34:37], v[34:35], off
	global_load_dwordx4 v[30:33], v[30:31], off
	global_load_dwordx4 v[48:51], v[48:49], off
	s_waitcnt vmcnt(4)
	v_mfma_f32_16x16x32_bf16 v[14:17], v[52:55], v[60:63], v[14:17]
	v_mfma_f32_16x16x32_bf16 v[10:13], v[56:59], v[60:63], v[10:13]
	v_mfma_f32_16x16x32_bf16 v[6:9], v[52:55], v[64:67], v[6:9]
	v_mfma_f32_16x16x32_bf16 v[2:5], v[56:59], v[64:67], v[2:5]
	s_branch .Lmy_sk1_loop

.Lmy_sk1_done:
.LBB0_723:
	s_lshl_b32 s6, s12, 12
	v_lshlrev_b32_e32 v18, 7, v157
	s_add_i32 s6, s6, 0
	v_add3_u32 v18, s6, v130, v18
	s_movk_i32 s6, 0x100
	v_cmp_gt_i32_e32 vcc, s6, v156
	ds_write_b128 v18, v[14:17]
	ds_write_b128 v18, v[10:13] offset:64
	ds_write_b128 v18, v[6:9] offset:2048
	ds_write_b128 v18, v[2:5] offset:2112
	s_waitcnt lgkmcnt(0)
	s_barrier
	s_and_saveexec_b64 s[18:19], vcc
	s_cbranch_execz .LBB0_728
	v_lshlrev_b32_e32 v2, 2, v156
	v_ashrrev_i32_e32 v12, 3, v156
	v_and_b32_e32 v13, 28, v2
	v_lshlrev_b32_e32 v2, 7, v12
	v_lshlrev_b32_e32 v3, 2, v13
	v_add3_u32 v14, 0, v2, v3
	ds_read_b128 v[2:5], v14
	ds_read_b128 v[6:9], v14 offset:4096
	s_movk_i32 s6, 0x5ff
	s_waitcnt lgkmcnt(0)
	v_pk_add_f32 v[8:9], v[4:5], v[8:9]
	v_pk_add_f32 v[6:7], v[2:3], v[6:7]
	ds_read_b128 v[2:5], v14 offset:8192
	s_waitcnt lgkmcnt(0)
	v_pk_add_f32 v[8:9], v[8:9], v[4:5]
	v_pk_add_f32 v[6:7], v[6:7], v[2:3]
	ds_read_b128 v[2:5], v14 offset:12288
	s_waitcnt lgkmcnt(0)
	v_pk_add_f32 v[8:9], v[8:9], v[4:5]
	v_pk_add_f32 v[6:7], v[6:7], v[2:3]
	ds_read_b128 v[2:5], v14 offset:16384
	s_waitcnt lgkmcnt(0)
	v_pk_add_f32 v[8:9], v[8:9], v[4:5]
	v_pk_add_f32 v[6:7], v[6:7], v[2:3]
	ds_read_b128 v[2:5], v14 offset:20480
	s_waitcnt lgkmcnt(0)
	v_pk_add_f32 v[8:9], v[8:9], v[4:5]
	v_pk_add_f32 v[6:7], v[6:7], v[2:3]
	ds_read_b128 v[2:5], v14 offset:24576
	s_waitcnt lgkmcnt(0)
	v_pk_add_f32 v[8:9], v[8:9], v[4:5]
	v_pk_add_f32 v[10:11], v[6:7], v[2:3]
	ds_read_b128 v[4:7], v14 offset:28672
	s_waitcnt lgkmcnt(0)
	v_pk_add_f32 v[2:3], v[8:9], v[6:7]
	v_add_u32_e32 v9, s7, v12
	v_pk_add_f32 v[6:7], v[10:11], v[4:5]
	v_add_u32_e32 v10, 0x2000, v9
	v_ashrrev_i32_e32 v11, 31, v10
	v_lshl_add_u64 v[4:5], v[10:11], 3, s[14:15]
	global_load_dwordx2 v[4:5], v[4:5], off
	v_or_b32_e32 v8, s9, v13
	s_waitcnt vmcnt(0)
	v_ffbh_u32_e32 v12, v5
	v_min_u32_e32 v12, 32, v12
	v_lshlrev_b64 v[4:5], v12, v[4:5]
	v_min_u32_e32 v4, 1, v4
	v_or_b32_e32 v4, v5, v4
	v_cvt_f32_u32_e32 v4, v4
	v_sub_u32_e32 v5, 32, v12
	v_ldexp_f32 v4, v4, v5
	v_mul_f32_e32 v4, 0x30800000, v4
	v_fmamk_f32 v4, v4, 0x3a000000, v1
	v_cmp_gt_f32_e32 vcc, s65, v4
	v_mul_f32_e32 v5, 0x4b800000, v4
	s_nop 0
	v_cndmask_b32_e32 v4, v4, v5, vcc
	v_rsq_f32_e32 v4, v4
	s_nop 0
	v_mul_f32_e32 v5, 0x45800000, v4
	v_cndmask_b32_e32 v12, v4, v5, vcc
	v_pk_mul_f32 v[4:5], v[2:3], v[12:13] op_sel_hi:[1,0]
	v_pk_mul_f32 v[2:3], v[6:7], v[12:13] op_sel_hi:[1,0]
	v_cmp_lt_i32_e32 vcc, s6, v8
	s_and_saveexec_b64 s[6:7], vcc
	s_xor_b64 s[14:15], exec, s[6:7]
	s_cbranch_execz .LBB0_726
	v_cvt_pk_bf16_f32 v2, v2, v3
	v_cvt_pk_bf16_f32 v3, v4, v5
	v_lshlrev_b64 v[4:5], 10, v[10:11]
	v_lshl_add_u64 v[4:5], s[10:11], 0, v[4:5]
	v_mov_b32_e32 v9, v181
	v_lshl_add_u64 v[4:5], v[8:9], 1, v[4:5]
	global_store_dwordx2 v[4:5], v[2:3], off offset:-3072

.LBB0_1558:
	s_ashr_i32 s25, s24, 31
	s_lshl_b64 s[28:29], s[24:25], 1
	v_lshl_add_u64 v[26:27], v[18:19], 0, s[28:29]
	v_lshl_add_u64 v[34:35], v[22:23], 0, s[28:29]
	v_lshl_add_u64 v[30:31], v[20:21], 0, s[28:29]
	v_lshl_add_u64 v[48:49], v[24:25], 0, s[28:29]
	global_load_dwordx4 v[26:29], v[26:27], off
	global_load_dwordx4 v[34:37], v[34:35], off
	global_load_dwordx4 v[30:33], v[30:31], off
	global_load_dwordx4 v[48:51], v[48:49], off
.Lmy_sk2_loop:
	s_add_i32 s21, s21, 8
	s_addk_i32 s24, 0x100
	s_ashr_i32 s25, s24, 31
	s_lshl_b64 s[28:29], s[24:25], 1
	s_cmp_gt_i32 s21, 55
	s_cbranch_scc1 .Lmy_sk2_lastx
	v_lshl_add_u64 v[52:53], v[18:19], 0, s[28:29]
	v_lshl_add_u64 v[56:57], v[22:23], 0, s[28:29]
	v_lshl_add_u64 v[60:61], v[20:21], 0, s[28:29]
	v_lshl_add_u64 v[64:65], v[24:25], 0, s[28:29]
	global_load_dwordx4 v[52:55], v[52:53], off
	global_load_dwordx4 v[56:59], v[56:57], off
	global_load_dwordx4 v[60:63], v[60:61], off
	global_load_dwordx4 v[64:67], v[64:65], off
	s_waitcnt vmcnt(4)
	v_mfma_f32_16x16x32_bf16 v[14:17], v[26:29], v[30:33], v[14:17]
	v_mfma_f32_16x16x32_bf16 v[10:13], v[34:37], v[30:33], v[10:13]
	v_mfma_f32_16x16x32_bf16 v[6:9], v[26:29], v[48:51], v[6:9]
	v_mfma_f32_16x16x32_bf16 v[2:5], v[34:37], v[48:51], v[2:5]
	s_add_i32 s21, s21, 8
	s_addk_i32 s24, 0x100
	s_ashr_i32 s25, s24, 31
	s_lshl_b64 s[28:29], s[24:25], 1
	s_cmp_gt_i32 s21, 55
	s_cbranch_scc1 .Lmy_sk2_lasty
	v_lshl_add_u64 v[26:27], v[18:19], 0, s[28:29]
	v_lshl_add_u64 v[34:35], v[22:23], 0, s[28:29]
	v_lshl_add_u64 v[30:31], v[20:21], 0, s[28:29]
	v_lshl_add_u64 v[48:49], v[24:25], 0, s[28:29]
	global_load_dwordx4 v[26:29], v[26:27], off
	global_load_dwordx4 v[34:37], v[34:35], off
	global_load_dwordx4 v[30:33], v[30:31], off
	global_load_dwordx4 v[48:51], v[48:49], off
	s_waitcnt vmcnt(4)
	v_mfma_f32_16x16x32_bf16 v[14:17], v[52:55], v[60:63], v[14:17]
	v_mfma_f32_16x16x32_bf16 v[10:13], v[56:59], v[60:63], v[10:13]
	v_mfma_f32_16x16x32_bf16 v[6:9], v[52:55], v[64:67], v[6:9]
	v_mfma_f32_16x16x32_bf16 v[2:5], v[56:59], v[64:67], v[2:5]
	s_branch .Lmy_sk2_loop

.Lmy_sk2_done:
.LBB0_1559:
	s_lshl_b32 s12, s12, 12
	v_lshlrev_b32_e32 v18, 7, v149
	s_add_i32 s12, s12, 0
	v_add3_u32 v18, s12, v130, v18
	s_movk_i32 s12, 0x100
	v_cmp_gt_i32_e32 vcc, s12, v148
	ds_write_b128 v18, v[14:17]
	ds_write_b128 v18, v[10:13] offset:64
	ds_write_b128 v18, v[6:9] offset:2048
	ds_write_b128 v18, v[2:5] offset:2112
	s_waitcnt lgkmcnt(0)
	s_barrier
	s_and_saveexec_b64 s[24:25], vcc
	s_cbranch_execz .LBB0_1562
	v_lshlrev_b32_e32 v2, 2, v148
	v_ashrrev_i32_e32 v10, 3, v148
	v_and_b32_e32 v11, 28, v2
	v_lshlrev_b32_e32 v2, 7, v10
	v_lshlrev_b32_e32 v3, 2, v11
	v_add3_u32 v12, 0, v2, v3
	ds_read_b128 v[2:5], v12
	ds_read_b128 v[6:9], v12 offset:4096
	s_waitcnt lgkmcnt(0)
	v_pk_add_f32 v[8:9], v[4:5], v[8:9]
	v_pk_add_f32 v[6:7], v[2:3], v[6:7]
	ds_read_b128 v[2:5], v12 offset:8192
	s_waitcnt lgkmcnt(0)
	v_pk_add_f32 v[8:9], v[8:9], v[4:5]
	v_pk_add_f32 v[6:7], v[6:7], v[2:3]
	ds_read_b128 v[2:5], v12 offset:12288
	s_waitcnt lgkmcnt(0)
	v_pk_add_f32 v[8:9], v[8:9], v[4:5]
	v_pk_add_f32 v[6:7], v[6:7], v[2:3]
	ds_read_b128 v[2:5], v12 offset:16384
	s_waitcnt lgkmcnt(0)
	v_pk_add_f32 v[8:9], v[8:9], v[4:5]
	v_pk_add_f32 v[6:7], v[6:7], v[2:3]
	ds_read_b128 v[2:5], v12 offset:20480
	s_waitcnt lgkmcnt(0)
	v_pk_add_f32 v[8:9], v[8:9], v[4:5]
	v_pk_add_f32 v[6:7], v[6:7], v[2:3]
	ds_read_b128 v[2:5], v12 offset:24576
	s_waitcnt lgkmcnt(0)
	v_pk_add_f32 v[8:9], v[8:9], v[4:5]
	v_pk_add_f32 v[6:7], v[6:7], v[2:3]
	ds_read_b128 v[2:5], v12 offset:28672
	s_waitcnt lgkmcnt(0)
	v_pk_add_f32 v[6:7], v[6:7], v[2:3]
	v_add_u32_e32 v2, s8, v10
	v_add_u32_e32 v2, 0x2000, v2
	v_ashrrev_i32_e32 v3, 31, v2
	v_pk_add_f32 v[4:5], v[8:9], v[4:5]
	v_or_b32_e32 v8, s9, v11
	v_lshlrev_b64 v[10:11], 12, v[2:3]
	v_lshl_add_u64 v[10:11], s[14:15], 0, v[10:11]
	v_ashrrev_i32_e32 v9, 31, v8
	v_lshl_add_u64 v[8:9], v[8:9], 1, v[10:11]
	global_load_dwordx2 v[10:11], v[8:9], off
	s_waitcnt vmcnt(0)
	v_lshlrev_b32_e32 v12, 16, v10
	v_and_b32_e32 v13, 0xffff0000, v10
	v_lshlrev_b32_e32 v10, 16, v11
	v_and_b32_e32 v11, 0xffff0000, v11
	v_pk_add_f32 v[4:5], v[4:5], v[10:11]
	v_pk_add_f32 v[6:7], v[6:7], v[12:13]
	s_nop 0
	v_cvt_pk_bf16_f32 v10, v6, v7
	v_cvt_pk_bf16_f32 v11, v4, v5
	v_mul_f32_e32 v7, v7, v7
	v_mul_f32_e32 v5, v5, v5
	v_fmac_f32_e32 v7, v6, v6
	v_fmac_f32_e32 v5, v4, v4
	v_and_b32_e32 v6, 64, v226
	v_add_f32_e32 v4, v7, v5
	v_xor_b32_e32 v5, 1, v226
	v_add_u32_e32 v6, 64, v6
	v_cmp_lt_i32_e32 vcc, v5, v6
	global_store_dwordx2 v[8:9], v[10:11], off
	s_nop 0
	v_cndmask_b32_e32 v5, v226, v5, vcc
	v_lshlrev_b32_e32 v5, 2, v5
	ds_bpermute_b32 v5, v5, v4
	s_waitcnt lgkmcnt(0)
	v_add_f32_e32 v4, v4, v5
	v_xor_b32_e32 v5, 2, v226
	v_cmp_lt_i32_e32 vcc, v5, v6
	s_nop 1
	v_cndmask_b32_e32 v5, v226, v5, vcc
	v_lshlrev_b32_e32 v5, 2, v5
	ds_bpermute_b32 v5, v5, v4
	s_waitcnt lgkmcnt(0)
	v_add_f32_e32 v4, v4, v5
	v_xor_b32_e32 v5, 4, v226
	v_cmp_lt_i32_e32 vcc, v5, v6
	v_mov_b32_e32 v6, v0
	s_nop 0
	v_cndmask_b32_e32 v5, v226, v5, vcc
	v_lshlrev_b32_e32 v5, 2, v5
	ds_bpermute_b32 v5, v5, v4
	v_and_b32_e32 v6, 7, v6
	v_cmp_eq_u32_e32 vcc, 0, v6
	s_and_b64 exec, exec, vcc
	s_cbranch_execz .LBB0_1562
	s_waitcnt lgkmcnt(0)
	v_add_f32_e32 v4, v4, v5
	v_mul_f32_e32 v4, 0x4e800000, v4
	v_trunc_f32_e32 v4, v4
	v_mul_f32_e64 v5, |v4|, s68
	v_floor_f32_e32 v5, v5
	v_fma_f32 v6, v5, s69, |v4|
	v_cvt_u32_f32_e32 v6, v6
	v_cvt_u32_f32_e32 v5, v5
	v_ashrrev_i32_e32 v7, 31, v4
	v_lshl_add_u64 v[2:3], v[2:3], 3, s[10:11]
	v_xor_b32_e32 v4, v6, v7
	v_xor_b32_e32 v5, v5, v7
	v_sub_co_u32_e32 v4, vcc, v4, v7
	s_nop 1
	v_subb_co_u32_e32 v5, vcc, v5, v7, vcc
	global_atomic_add_x2 v[2:3], v[4:5], off

.Lmy_sk3_done:
.LBB0_1609:
	s_lshl_b32 s6, s9, 12
	v_lshlrev_b32_e32 v18, 7, v149
	s_add_i32 s6, s6, 0
	v_add3_u32 v18, s6, v130, v18
	s_movk_i32 s6, 0x100
	v_cmp_gt_i32_e32 vcc, s6, v148
	ds_write_b128 v18, v[14:17]
	ds_write_b128 v18, v[10:13] offset:64
	ds_write_b128 v18, v[6:9] offset:2048
	ds_write_b128 v18, v[2:5] offset:2112
	s_waitcnt vmcnt(0) lgkmcnt(0)
	s_barrier
	s_and_saveexec_b64 s[18:19], vcc
	s_cbranch_execz .LBB0_1612
	v_lshlrev_b32_e32 v2, 2, v148
	v_ashrrev_i32_e32 v10, 3, v148
	v_and_b32_e32 v11, 28, v2
	v_lshlrev_b32_e32 v2, 7, v10
	v_lshlrev_b32_e32 v3, 2, v11
	v_add3_u32 v12, 0, v2, v3
	ds_read_b128 v[2:5], v12
	ds_read_b128 v[6:9], v12 offset:4096
	s_waitcnt lgkmcnt(0)
	v_pk_add_f32 v[8:9], v[4:5], v[8:9]
	v_pk_add_f32 v[6:7], v[2:3], v[6:7]
	ds_read_b128 v[2:5], v12 offset:8192
	s_waitcnt lgkmcnt(0)
	v_pk_add_f32 v[8:9], v[8:9], v[4:5]
	v_pk_add_f32 v[6:7], v[6:7], v[2:3]
	ds_read_b128 v[2:5], v12 offset:12288
	s_waitcnt lgkmcnt(0)
	v_pk_add_f32 v[8:9], v[8:9], v[4:5]
	v_pk_add_f32 v[6:7], v[6:7], v[2:3]
	ds_read_b128 v[2:5], v12 offset:16384
	s_waitcnt lgkmcnt(0)
	v_pk_add_f32 v[8:9], v[8:9], v[4:5]
	v_pk_add_f32 v[6:7], v[6:7], v[2:3]
	ds_read_b128 v[2:5], v12 offset:20480
	s_waitcnt lgkmcnt(0)
	v_pk_add_f32 v[8:9], v[8:9], v[4:5]
	v_pk_add_f32 v[6:7], v[6:7], v[2:3]
	ds_read_b128 v[2:5], v12 offset:24576
	s_waitcnt lgkmcnt(0)
	v_pk_add_f32 v[8:9], v[8:9], v[4:5]
	v_pk_add_f32 v[6:7], v[6:7], v[2:3]
	ds_read_b128 v[2:5], v12 offset:28672
	s_waitcnt lgkmcnt(0)
	v_pk_add_f32 v[6:7], v[6:7], v[2:3]
	v_add_u32_e32 v2, s7, v10
	v_add_u32_e32 v2, 0x2000, v2
	v_ashrrev_i32_e32 v3, 31, v2
	v_pk_add_f32 v[4:5], v[8:9], v[4:5]
	v_or_b32_e32 v8, s8, v11
	v_lshlrev_b64 v[10:11], 12, v[2:3]
	v_lshl_add_u64 v[10:11], s[14:15], 0, v[10:11]
	v_ashrrev_i32_e32 v9, 31, v8
	v_lshl_add_u64 v[8:9], v[8:9], 1, v[10:11]
	global_load_dwordx2 v[10:11], v[8:9], off
	s_waitcnt vmcnt(0)
	v_lshlrev_b32_e32 v12, 16, v10
	v_and_b32_e32 v13, 0xffff0000, v10
	v_lshlrev_b32_e32 v10, 16, v11
	v_and_b32_e32 v11, 0xffff0000, v11
	v_pk_add_f32 v[4:5], v[4:5], v[10:11]
	v_pk_add_f32 v[6:7], v[6:7], v[12:13]
	s_nop 0
	v_cvt_pk_bf16_f32 v10, v6, v7
	v_cvt_pk_bf16_f32 v11, v4, v5
	v_mul_f32_e32 v7, v7, v7
	v_mul_f32_e32 v5, v5, v5
	v_fmac_f32_e32 v7, v6, v6
	v_fmac_f32_e32 v5, v4, v4
	v_and_b32_e32 v6, 64, v226
	v_add_f32_e32 v4, v7, v5
	v_xor_b32_e32 v5, 1, v226
	v_add_u32_e32 v6, 64, v6
	v_cmp_lt_i32_e32 vcc, v5, v6
	global_store_dwordx2 v[8:9], v[10:11], off
	s_nop 0
	v_cndmask_b32_e32 v5, v226, v5, vcc
	v_lshlrev_b32_e32 v5, 2, v5
	ds_bpermute_b32 v5, v5, v4
	s_waitcnt lgkmcnt(0)
	v_add_f32_e32 v4, v4, v5
	v_xor_b32_e32 v5, 2, v226
	v_cmp_lt_i32_e32 vcc, v5, v6
	s_nop 1
	v_cndmask_b32_e32 v5, v226, v5, vcc
	v_lshlrev_b32_e32 v5, 2, v5
	ds_bpermute_b32 v5, v5, v4
	s_waitcnt lgkmcnt(0)
	v_add_f32_e32 v4, v4, v5
	v_xor_b32_e32 v5, 4, v226
	v_cmp_lt_i32_e32 vcc, v5, v6
	v_mov_b32_e32 v6, v0
	s_nop 0
	v_cndmask_b32_e32 v5, v226, v5, vcc
	v_lshlrev_b32_e32 v5, 2, v5
	ds_bpermute_b32 v5, v5, v4
	v_and_b32_e32 v6, 7, v6
	v_cmp_eq_u32_e32 vcc, 0, v6
	s_and_b64 exec, exec, vcc
	s_cbranch_execz .LBB0_1612
	s_waitcnt lgkmcnt(0)
	v_add_f32_e32 v4, v4, v5
	v_mul_f32_e32 v4, 0x4e800000, v4
	v_trunc_f32_e32 v4, v4
	v_mul_f32_e64 v5, |v4|, s68
	v_floor_f32_e32 v5, v5
	v_fma_f32 v6, v5, s69, |v4|
	v_cvt_u32_f32_e32 v6, v6
	v_cvt_u32_f32_e32 v5, v5
	v_ashrrev_i32_e32 v7, 31, v4
	v_lshl_add_u64 v[2:3], v[2:3], 3, s[10:11]
	v_xor_b32_e32 v4, v6, v7
	v_xor_b32_e32 v5, v5, v7
	v_sub_co_u32_e32 v4, vcc, v4, v7
	s_nop 1
	v_subb_co_u32_e32 v5, vcc, v5, v7, vcc
	global_atomic_add_x2 v[2:3], v[4:5], off

.LBB0_1878:
	s_ashr_i32 s23, s22, 31
	s_lshl_b64 s[26:27], s[22:23], 1
	v_lshl_add_u64 v[34:35], v[20:21], 0, s[26:27]
	v_lshl_add_u64 v[42:43], v[24:25], 0, s[26:27]
	v_lshl_add_u64 v[38:39], v[22:23], 0, s[26:27]
	v_lshl_add_u64 v[48:49], v[26:27], 0, s[26:27]
	global_load_dwordx4 v[34:37], v[34:35], off
	global_load_dwordx4 v[42:45], v[42:43], off
	global_load_dwordx4 v[38:41], v[38:39], off
	global_load_dwordx4 v[48:51], v[48:49], off
.Lmy_sk4_loop:
	s_add_i32 s9, s9, 8
	s_addk_i32 s22, 0x100
	s_ashr_i32 s23, s22, 31
	s_lshl_b64 s[26:27], s[22:23], 1
	s_cmpk_gt_i32 s9, 0xa3
	s_cbranch_scc1 .Lmy_sk4_lastx
	v_lshl_add_u64 v[52:53], v[20:21], 0, s[26:27]
	v_lshl_add_u64 v[56:57], v[24:25], 0, s[26:27]
	v_lshl_add_u64 v[60:61], v[22:23], 0, s[26:27]
	v_lshl_add_u64 v[64:65], v[26:27], 0, s[26:27]
	global_load_dwordx4 v[52:55], v[52:53], off
	global_load_dwordx4 v[56:59], v[56:57], off
	global_load_dwordx4 v[60:63], v[60:61], off
	global_load_dwordx4 v[64:67], v[64:65], off
	s_waitcnt vmcnt(4)
	v_mfma_f32_16x16x32_bf16 v[14:17], v[34:37], v[38:41], v[14:17]
	v_mfma_f32_16x16x32_bf16 v[10:13], v[42:45], v[38:41], v[10:13]
	v_mfma_f32_16x16x32_bf16 v[6:9], v[34:37], v[48:51], v[6:9]
	v_mfma_f32_16x16x32_bf16 v[2:5], v[42:45], v[48:51], v[2:5]
	s_add_i32 s9, s9, 8
	s_addk_i32 s22, 0x100
	s_ashr_i32 s23, s22, 31
	s_lshl_b64 s[26:27], s[22:23], 1
	s_cmpk_gt_i32 s9, 0xa3
	s_cbranch_scc1 .Lmy_sk4_lasty
	v_lshl_add_u64 v[34:35], v[20:21], 0, s[26:27]
	v_lshl_add_u64 v[42:43], v[24:25], 0, s[26:27]
	v_lshl_add_u64 v[38:39], v[22:23], 0, s[26:27]
	v_lshl_add_u64 v[48:49], v[26:27], 0, s[26:27]
	global_load_dwordx4 v[34:37], v[34:35], off
	global_load_dwordx4 v[42:45], v[42:43], off
	global_load_dwordx4 v[38:41], v[38:39], off
	global_load_dwordx4 v[48:51], v[48:49], off
	s_waitcnt vmcnt(4)
	v_mfma_f32_16x16x32_bf16 v[14:17], v[52:55], v[60:63], v[14:17]
	v_mfma_f32_16x16x32_bf16 v[10:13], v[56:59], v[60:63], v[10:13]
	v_mfma_f32_16x16x32_bf16 v[6:9], v[52:55], v[64:67], v[6:9]
	v_mfma_f32_16x16x32_bf16 v[2:5], v[56:59], v[64:67], v[2:5]
	s_branch .Lmy_sk4_loop
.Lmy_sk4_lastx:
	s_waitcnt vmcnt(0)
	v_mfma_f32_16x16x32_bf16 v[14:17], v[34:37], v[38:41], v[14:17]
	v_mfma_f32_16x16x32_bf16 v[10:13], v[42:45], v[38:41], v[10:13]
	v_mfma_f32_16x16x32_bf16 v[6:9], v[34:37], v[48:51], v[6:9]
	v_mfma_f32_16x16x32_bf16 v[2:5], v[42:45], v[48:51], v[2:5]
	s_branch .Lmy_sk4_done

.Lmy_sk4_done:
.LBB0_1879:
	v_lshl_add_u32 v19, s8, 12, v30
	s_nop 0
	ds_write_b128 v19, v[14:17]
	ds_write_b128 v19, v[10:13] offset:64
	s_nop 1
	ds_write_b128 v19, v[6:9] offset:2048
	ds_write_b128 v19, v[2:5] offset:2112
	s_waitcnt lgkmcnt(0)
	s_barrier
	s_and_saveexec_b64 s[22:23], s[38:39]
	s_cbranch_execz .LBB0_1869
	ds_read_b128 v[2:5], v32
	ds_read_b128 v[6:9], v32 offset:4096
	v_or_b32_e32 v10, s7, v31
	v_lshlrev_b32_e32 v180, 1, v10
	s_waitcnt lgkmcnt(0)
	v_pk_add_f32 v[8:9], v[4:5], v[8:9]
	v_pk_add_f32 v[6:7], v[2:3], v[6:7]
	ds_read_b128 v[2:5], v32 offset:8192
	s_waitcnt lgkmcnt(0)
	v_pk_add_f32 v[8:9], v[8:9], v[4:5]
	v_pk_add_f32 v[6:7], v[6:7], v[2:3]
	ds_read_b128 v[2:5], v32 offset:12288
	s_waitcnt lgkmcnt(0)
	v_pk_add_f32 v[8:9], v[8:9], v[4:5]
	v_pk_add_f32 v[6:7], v[6:7], v[2:3]
	ds_read_b128 v[2:5], v32 offset:16384
	s_waitcnt lgkmcnt(0)
	v_pk_add_f32 v[8:9], v[8:9], v[4:5]
	v_pk_add_f32 v[6:7], v[6:7], v[2:3]
	ds_read_b128 v[2:5], v32 offset:20480
	s_waitcnt lgkmcnt(0)
	v_pk_add_f32 v[8:9], v[8:9], v[4:5]
	v_pk_add_f32 v[6:7], v[6:7], v[2:3]
	ds_read_b128 v[2:5], v32 offset:24576
	s_waitcnt lgkmcnt(0)
	v_pk_add_f32 v[8:9], v[8:9], v[4:5]
	v_pk_add_f32 v[6:7], v[6:7], v[2:3]
	ds_read_b128 v[2:5], v32 offset:28672
	s_waitcnt lgkmcnt(0)
	v_pk_add_f32 v[6:7], v[6:7], v[2:3]
	v_add_u32_e32 v2, s6, v33
	v_ashrrev_i32_e32 v3, 31, v2
	v_pk_add_f32 v[4:5], v[8:9], v[4:5]
	v_lshlrev_b64 v[8:9], 12, v[2:3]
	v_lshl_add_u64 v[8:9], s[14:15], 0, v[8:9]
	v_lshl_add_u64 v[8:9], v[8:9], 0, v[180:181]
	global_load_dwordx2 v[10:11], v[8:9], off
	s_waitcnt vmcnt(0)
	v_lshlrev_b32_e32 v12, 16, v10
	v_and_b32_e32 v13, 0xffff0000, v10
	v_lshlrev_b32_e32 v10, 16, v11
	v_and_b32_e32 v11, 0xffff0000, v11
	v_pk_add_f32 v[4:5], v[4:5], v[10:11]
	v_pk_add_f32 v[6:7], v[6:7], v[12:13]
	s_nop 0
	v_cvt_pk_bf16_f32 v10, v6, v7
	v_cvt_pk_bf16_f32 v11, v4, v5
	v_mul_f32_e32 v7, v7, v7
	v_mul_f32_e32 v5, v5, v5
	v_fmac_f32_e32 v7, v6, v6
	v_fmac_f32_e32 v5, v4, v4
	v_and_b32_e32 v6, 64, v226
	v_add_f32_e32 v4, v7, v5
	v_xor_b32_e32 v5, 1, v226
	v_add_u32_e32 v6, 64, v6
	v_cmp_lt_i32_e32 vcc, v5, v6
	global_store_dwordx2 v[8:9], v[10:11], off
	s_nop 0
	v_cndmask_b32_e32 v5, v226, v5, vcc
	v_lshlrev_b32_e32 v5, 2, v5
	ds_bpermute_b32 v5, v5, v4
	s_waitcnt lgkmcnt(0)
	v_add_f32_e32 v4, v4, v5
	v_xor_b32_e32 v5, 2, v226
	v_cmp_lt_i32_e32 vcc, v5, v6
	s_nop 1
	v_cndmask_b32_e32 v5, v226, v5, vcc
	v_lshlrev_b32_e32 v5, 2, v5
	ds_bpermute_b32 v5, v5, v4
	s_waitcnt lgkmcnt(0)
	v_add_f32_e32 v4, v4, v5
	v_xor_b32_e32 v5, 4, v226
	v_cmp_lt_i32_e32 vcc, v5, v6
	v_mov_b32_e32 v6, v0
	s_nop 0
	v_cndmask_b32_e32 v5, v226, v5, vcc
	v_lshlrev_b32_e32 v5, 2, v5
	ds_bpermute_b32 v5, v5, v4
	v_and_b32_e32 v6, 7, v6
	v_cmp_eq_u32_e32 vcc, 0, v6
	s_and_b64 exec, exec, vcc
	s_cbranch_execz .LBB0_1869
	s_waitcnt lgkmcnt(0)
	v_add_f32_e32 v4, v4, v5
	v_mul_f32_e32 v4, 0x4e800000, v4
	v_trunc_f32_e32 v4, v4
	v_mul_f32_e64 v5, |v4|, s68
	v_floor_f32_e32 v5, v5
	v_fma_f32 v6, v5, s69, |v4|
	v_cvt_u32_f32_e32 v6, v6
	v_cvt_u32_f32_e32 v5, v5
	v_ashrrev_i32_e32 v7, 31, v4
	v_lshl_add_u64 v[2:3], v[2:3], 3, s[18:19]
	v_xor_b32_e32 v4, v6, v7
	v_xor_b32_e32 v5, v5, v7
	v_sub_co_u32_e32 v4, vcc, v4, v7
	s_nop 1
	v_subb_co_u32_e32 v5, vcc, v5, v7, vcc
	global_atomic_add_x2 v[2:3], v[4:5], off
	s_branch .LBB0_1869
